# GEMM2: half of the partner groups start ~7us later (de-synchronise TA-bound K-loops from HBM-bound epilogues)
# baseline (speedup 1.0000x reference)
.LBB0_566:
	s_or_b64 exec, exec, s[0:1]
	s_cmpk_gt_i32 s97, 0xbf
	s_waitcnt lgkmcnt(0)
	s_barrier
	s_cbranch_scc1 .LBB0_588
	s_bitcmp1_b32 s97, 5
	s_cbranch_scc0 .Lg2_nodelay
	s_sleep 127
	s_sleep 127
.Lg2_nodelay:
	v_ashrrev_i32_e32 v146, 3, v0
	v_lshlrev_b32_e32 v2, 4, v0
	v_xor_b32_e32 v3, v2, v0
	v_lshlrev_b32_e32 v7, 7, v146
	s_movk_i32 s0, 0x70
	v_bfe_u32 v6, v0, 4, 2
	v_and_or_b32 v3, v3, s0, v7
	v_bfe_u32 v8, v0, 6, 1
	v_add_u32_e32 v147, 16, v3
	v_lshlrev_b32_e32 v3, 2, v6
	s_waitcnt vmcnt(0)
	v_and_b32_e32 v10, 64, v1
	v_lshl_or_b32 v149, v8, 6, v3
	v_xor_b32_e32 v3, 16, v1
	v_add_u32_e32 v10, 64, v10
	v_cmp_lt_i32_e32 vcc, v3, v10
	v_bfe_u32 v4, v0, 1, 3
	v_lshrrev_b32_e32 v5, 4, v0
	v_cndmask_b32_e32 v3, v1, v3, vcc
	v_lshlrev_b32_e32 v150, 2, v3
	v_xor_b32_e32 v3, 32, v1
	v_cmp_lt_i32_e32 vcc, v3, v10
	v_and_b32_e32 v7, 15, v0
	v_ashrrev_i32_e32 v9, 7, v0
	v_cndmask_b32_e32 v1, v1, v3, vcc
	v_cmp_eq_u32_e64 s[2:3], 0, v0
	v_bitop3_b32 v0, v5, v4, 3 bitop3:0x6c
	v_and_b32_e32 v112, 0x70, v2
	v_lshlrev_b32_e32 v2, 6, v9
	v_lshlrev_b32_e32 v151, 2, v1
	v_lshl_add_u32 v0, v0, 4, 16
	v_lshlrev_b32_e32 v1, 13, v8
	v_lshlrev_b32_e32 v9, 13, v9
	v_add_u32_e32 v8, v0, v1
	v_add_u32_e32 v10, v0, v9
	v_bitop3_b32 v0, v6, v4, 4 bitop3:0x36
	s_ashr_i32 s12, s62, 3
	v_readlane_b32 s0, v254, 43
	v_mov_b32_e32 v113, 0
	v_ashrrev_i32_e32 v3, 31, v2
	v_lshl_add_u32 v0, v0, 4, 16
	s_mul_i32 s13, s0, 24
	v_lshl_add_u64 v[114:115], s[48:49], 0, v[112:113]
	v_lshl_add_u64 v[116:117], s[46:47], 0, v[112:113]
	v_cmp_eq_u32_e64 s[0:1], 0, v6
	v_lshlrev_b32_e32 v5, 7, v7
	v_add_u32_e32 v4, v0, v1
	v_add_u32_e32 v6, v0, v9
	s_add_u32 s14, s38, 0xfe000000
	v_lshl_add_u64 v[0:1], v[2:3], 2, s[92:93]
	v_lshlrev_b32_e32 v112, 2, v7
	v_or_b32_e32 v148, v2, v7
	s_addc_u32 s15, s39, -1
	v_lshl_add_u64 v[118:119], v[0:1], 0, v[112:113]
	s_mov_b32 s16, 0x10000
	s_mov_b32 s17, 0x20000
	s_mov_b32 s18, 0x30000
	v_add_u32_e32 v152, v8, v5
	v_add_u32_e32 v153, v10, v5
	v_add_u32_e32 v154, v4, v5
	v_add_u32_e32 v155, v6, v5
	v_mov_b32_e32 v156, 0x358637bd
	s_mov_b32 s19, 0x800000
	s_branch .LBB0_569
